# gate-up epilogue: bias folded into first fma, carry-ins via 2 ds_read_b128 (straight-line); accumulator zeroing with v_mov_b64 in all 5 GEMM unit headers
# speedup vs baseline: 1.0133x; 1.0056x over previous
.LBB0_131:
	s_ashr_i32 s57, s56, 31
	s_lshl_b64 s[58:59], s[56:57], 21
	s_add_u32 s58, s8, s58
	s_addc_u32 s59, s9, s59
	s_and_b64 s[70:71], s[0:1], exec
	s_cselect_b32 s57, s59, s77
	s_cselect_b32 s95, s58, s76
	s_ashr_i32 s55, s54, 31
	s_lshl_b64 s[70:71], s[54:55], 21
	s_add_u32 s70, s14, s70
	s_addc_u32 s71, s15, s71
	s_and_b64 s[78:79], s[0:1], exec
	s_cselect_b32 s55, s71, s75
	s_cselect_b32 s96, s70, s74
	s_add_u32 s97, s74, 0x1000
	s_addc_u32 vcc_lo, s75, 0
	s_add_u32 s74, s76, 0x100080
	v_mov_b64_e32 v[0:1], 0
	v_mov_b64_e32 v[2:3], 0
	v_mov_b64_e32 v[4:5], 0
	v_mov_b64_e32 v[6:7], 0
	v_mov_b64_e32 v[8:9], 0
	v_mov_b64_e32 v[10:11], 0
	v_mov_b64_e32 v[12:13], 0
	v_mov_b64_e32 v[14:15], 0
	v_mov_b64_e32 v[16:17], 0
	v_mov_b64_e32 v[18:19], 0
	v_mov_b64_e32 v[20:21], 0
	v_mov_b64_e32 v[22:23], 0
	v_mov_b64_e32 v[24:25], 0
	v_mov_b64_e32 v[26:27], 0
	v_mov_b64_e32 v[28:29], 0
	v_mov_b64_e32 v[30:31], 0
	v_mov_b64_e32 v[32:33], 0
	v_mov_b64_e32 v[34:35], 0
	v_mov_b64_e32 v[36:37], 0
	v_mov_b64_e32 v[38:39], 0
	v_mov_b64_e32 v[40:41], 0
	v_mov_b64_e32 v[42:43], 0
	v_mov_b64_e32 v[44:45], 0
	v_mov_b64_e32 v[46:47], 0
	v_mov_b64_e32 v[48:49], 0
	v_mov_b64_e32 v[50:51], 0
	v_mov_b64_e32 v[52:53], 0
	v_mov_b64_e32 v[54:55], 0
	v_mov_b64_e32 v[56:57], 0
	v_mov_b64_e32 v[58:59], 0
	v_mov_b64_e32 v[60:61], 0
	v_mov_b64_e32 v[62:63], 0
	v_mov_b64_e32 v[64:65], 0
	v_mov_b64_e32 v[66:67], 0
	v_mov_b64_e32 v[68:69], 0
	v_mov_b64_e32 v[70:71], 0
	v_mov_b64_e32 v[72:73], 0
	v_mov_b64_e32 v[74:75], 0
	v_mov_b64_e32 v[76:77], 0
	v_mov_b64_e32 v[78:79], 0
	v_mov_b64_e32 v[80:81], 0
	v_mov_b64_e32 v[82:83], 0
	v_mov_b64_e32 v[84:85], 0
	v_mov_b64_e32 v[86:87], 0
	v_mov_b64_e32 v[88:89], 0
	v_mov_b64_e32 v[90:91], 0
	v_mov_b64_e32 v[92:93], 0
	v_mov_b64_e32 v[94:95], 0
	v_mov_b64_e32 v[96:97], 0
	v_mov_b64_e32 v[98:99], 0
	v_mov_b64_e32 v[100:101], 0
	v_mov_b64_e32 v[102:103], 0
	v_mov_b64_e32 v[104:105], 0
	v_mov_b64_e32 v[106:107], 0
	v_mov_b64_e32 v[108:109], 0
	v_mov_b64_e32 v[110:111], 0
	v_mov_b64_e32 v[112:113], 0
	v_mov_b64_e32 v[114:115], 0
	v_mov_b64_e32 v[116:117], 0
	v_mov_b64_e32 v[118:119], 0
	v_mov_b64_e32 v[120:121], 0
	v_mov_b64_e32 v[122:123], 0
	v_mov_b64_e32 v[124:125], 0
	v_mov_b64_e32 v[126:127], 0
	s_addc_u32 s75, s77, 0
	s_mov_b32 vcc_hi, -2

.LBB0_431:
	s_add_i32 s82, s82, 1
	s_mov_b32 s33, s0
	s_mov_b32 s91, s0
	s_mul_i32 s0, s82, s30
	s_mov_b64 s[70:71], s[4:5]
	s_add_i32 s4, s0, s2
	s_cmpk_lt_i32 s4, 0x200
	s_cselect_b64 s[58:59], -1, 0
	s_lshl_b32 s0, s4, 3
	s_mov_b64 s[16:17], s[38:39]
	s_mov_b32 s3, s78
	s_mov_b32 s38, s89
	s_mov_b32 s90, s78
	s_and_b32 s89, s0, 0xfffffc00
	s_ashr_i32 s0, s4, 6
	s_and_b32 s78, s4, 63
	s_and_b64 s[4:5], s[58:59], exec
	s_cselect_b32 s5, s89, s38
	s_cselect_b32 s38, s78, s3
	s_cselect_b32 s4, s0, s33
	s_ashr_i32 s39, s38, 31
	s_lshl_b64 s[38:39], s[38:39], 20
	s_add_u32 s3, s76, s38
	s_addc_u32 s33, s77, s39
	s_ashr_i32 s39, s5, 31
	s_add_u32 s38, s3, s5
	s_addc_u32 s39, s33, s39
	s_and_b64 s[72:73], s[58:59], exec
	s_cselect_b32 s93, s39, s17
	s_cselect_b32 s94, s38, s16
	s_ashr_i32 s5, s4, 31
	s_lshl_b64 s[4:5], s[4:5], 18
	s_add_u32 s4, s12, s4
	s_addc_u32 s5, s13, s5
	s_and_b64 s[72:73], s[58:59], exec
	s_cselect_b32 s95, s5, s71
	s_cselect_b32 s96, s4, s70
	s_add_u32 s97, s70, 0x1000
	s_addc_u32 vcc_lo, s71, 0
	s_add_u32 s70, s16, 0x80080
	v_mov_b64_e32 v[0:1], 0
	v_mov_b64_e32 v[2:3], 0
	v_mov_b64_e32 v[4:5], 0
	v_mov_b64_e32 v[6:7], 0
	v_mov_b64_e32 v[8:9], 0
	v_mov_b64_e32 v[10:11], 0
	v_mov_b64_e32 v[12:13], 0
	v_mov_b64_e32 v[14:15], 0
	v_mov_b64_e32 v[16:17], 0
	v_mov_b64_e32 v[18:19], 0
	v_mov_b64_e32 v[20:21], 0
	v_mov_b64_e32 v[22:23], 0
	v_mov_b64_e32 v[24:25], 0
	v_mov_b64_e32 v[26:27], 0
	v_mov_b64_e32 v[28:29], 0
	v_mov_b64_e32 v[30:31], 0
	v_mov_b64_e32 v[32:33], 0
	v_mov_b64_e32 v[34:35], 0
	v_mov_b64_e32 v[36:37], 0
	v_mov_b64_e32 v[38:39], 0
	v_mov_b64_e32 v[40:41], 0
	v_mov_b64_e32 v[42:43], 0
	v_mov_b64_e32 v[44:45], 0
	v_mov_b64_e32 v[46:47], 0
	v_mov_b64_e32 v[48:49], 0
	v_mov_b64_e32 v[50:51], 0
	v_mov_b64_e32 v[52:53], 0
	v_mov_b64_e32 v[54:55], 0
	v_mov_b64_e32 v[56:57], 0
	v_mov_b64_e32 v[58:59], 0
	v_mov_b64_e32 v[60:61], 0
	v_mov_b64_e32 v[62:63], 0
	v_mov_b64_e32 v[64:65], 0
	v_mov_b64_e32 v[66:67], 0
	v_mov_b64_e32 v[68:69], 0
	v_mov_b64_e32 v[70:71], 0
	v_mov_b64_e32 v[72:73], 0
	v_mov_b64_e32 v[74:75], 0
	v_mov_b64_e32 v[76:77], 0
	v_mov_b64_e32 v[78:79], 0
	v_mov_b64_e32 v[80:81], 0
	v_mov_b64_e32 v[82:83], 0
	v_mov_b64_e32 v[84:85], 0
	v_mov_b64_e32 v[86:87], 0
	v_mov_b64_e32 v[88:89], 0
	v_mov_b64_e32 v[90:91], 0
	v_mov_b64_e32 v[92:93], 0
	v_mov_b64_e32 v[94:95], 0
	v_mov_b64_e32 v[96:97], 0
	v_mov_b64_e32 v[98:99], 0
	v_mov_b64_e32 v[100:101], 0
	v_mov_b64_e32 v[102:103], 0
	v_mov_b64_e32 v[104:105], 0
	v_mov_b64_e32 v[106:107], 0
	v_mov_b64_e32 v[108:109], 0
	v_mov_b64_e32 v[110:111], 0
	v_mov_b64_e32 v[112:113], 0
	v_mov_b64_e32 v[114:115], 0
	v_mov_b64_e32 v[116:117], 0
	v_mov_b64_e32 v[118:119], 0
	v_mov_b64_e32 v[120:121], 0
	v_mov_b64_e32 v[122:123], 0
	v_mov_b64_e32 v[124:125], 0
	v_mov_b64_e32 v[126:127], 0
	s_addc_u32 s71, s17, 0
	s_mov_b32 vcc_hi, -2
	s_waitcnt vmcnt(0)

.LBB0_512:
	s_ashr_i32 s43, s42, 31
	s_lshl_b64 s[16:17], s[42:43], 21
	s_add_u32 s44, s8, s16
	s_addc_u32 s45, s9, s17
	s_and_b64 s[16:17], s[6:7], exec
	s_cselect_b32 s43, s45, s59
	s_cselect_b32 s49, s44, s58
	s_ashr_i32 s41, s40, 31
	s_lshl_b64 s[16:17], s[40:41], 21
	s_add_u32 s46, s10, s16
	s_addc_u32 s47, s11, s17
	s_and_b64 s[16:17], s[6:7], exec
	s_cselect_b32 s41, s47, s57
	s_cselect_b32 s55, s46, s56
	s_add_u32 s80, s56, 0x1000
	s_addc_u32 s81, s57, 0
	s_add_u32 s56, s58, 0x100080
	v_mov_b64_e32 v[0:1], 0
	v_mov_b64_e32 v[2:3], 0
	v_mov_b64_e32 v[4:5], 0
	v_mov_b64_e32 v[6:7], 0
	v_mov_b64_e32 v[8:9], 0
	v_mov_b64_e32 v[10:11], 0
	v_mov_b64_e32 v[12:13], 0
	v_mov_b64_e32 v[14:15], 0
	v_mov_b64_e32 v[16:17], 0
	v_mov_b64_e32 v[18:19], 0
	v_mov_b64_e32 v[20:21], 0
	v_mov_b64_e32 v[22:23], 0
	v_mov_b64_e32 v[24:25], 0
	v_mov_b64_e32 v[26:27], 0
	v_mov_b64_e32 v[28:29], 0
	v_mov_b64_e32 v[30:31], 0
	v_mov_b64_e32 v[32:33], 0
	v_mov_b64_e32 v[34:35], 0
	v_mov_b64_e32 v[36:37], 0
	v_mov_b64_e32 v[38:39], 0
	v_mov_b64_e32 v[40:41], 0
	v_mov_b64_e32 v[42:43], 0
	v_mov_b64_e32 v[44:45], 0
	v_mov_b64_e32 v[46:47], 0
	v_mov_b64_e32 v[48:49], 0
	v_mov_b64_e32 v[50:51], 0
	v_mov_b64_e32 v[52:53], 0
	v_mov_b64_e32 v[54:55], 0
	v_mov_b64_e32 v[56:57], 0
	v_mov_b64_e32 v[58:59], 0
	v_mov_b64_e32 v[60:61], 0
	v_mov_b64_e32 v[62:63], 0
	v_mov_b64_e32 v[64:65], 0
	v_mov_b64_e32 v[66:67], 0
	v_mov_b64_e32 v[68:69], 0
	v_mov_b64_e32 v[70:71], 0
	v_mov_b64_e32 v[72:73], 0
	v_mov_b64_e32 v[74:75], 0
	v_mov_b64_e32 v[76:77], 0
	v_mov_b64_e32 v[78:79], 0
	v_mov_b64_e32 v[80:81], 0
	v_mov_b64_e32 v[82:83], 0
	v_mov_b64_e32 v[84:85], 0
	v_mov_b64_e32 v[86:87], 0
	v_mov_b64_e32 v[88:89], 0
	v_mov_b64_e32 v[90:91], 0
	v_mov_b64_e32 v[92:93], 0
	v_mov_b64_e32 v[94:95], 0
	v_mov_b64_e32 v[96:97], 0
	v_mov_b64_e32 v[98:99], 0
	v_mov_b64_e32 v[100:101], 0
	v_mov_b64_e32 v[102:103], 0
	v_mov_b64_e32 v[104:105], 0
	v_mov_b64_e32 v[106:107], 0
	v_mov_b64_e32 v[108:109], 0
	v_mov_b64_e32 v[110:111], 0
	v_mov_b64_e32 v[112:113], 0
	v_mov_b64_e32 v[114:115], 0
	v_mov_b64_e32 v[116:117], 0
	v_mov_b64_e32 v[118:119], 0
	v_mov_b64_e32 v[120:121], 0
	v_mov_b64_e32 v[122:123], 0
	v_mov_b64_e32 v[124:125], 0
	v_mov_b64_e32 v[126:127], 0
	s_addc_u32 s57, s59, 0
	s_mov_b32 s82, -2
	s_waitcnt lgkmcnt(0)

.LBB0_638:
	s_ashr_i32 s55, s54, 31
	s_lshl_b64 s[16:17], s[54:55], 21
	s_add_u32 s56, s22, s16
	s_addc_u32 s57, s23, s17
	s_and_b64 s[16:17], s[8:9], exec
	s_cselect_b32 s11, s57, s15
	s_cselect_b32 s13, s56, s14
	s_ashr_i32 s53, s52, 31
	s_lshl_b64 s[16:17], s[52:53], 21
	s_add_u32 s58, s68, s16
	s_addc_u32 s59, s69, s17
	s_and_b64 s[16:17], s[8:9], exec
	s_cselect_b32 s53, s59, s61
	s_cselect_b32 s55, s58, s60
	s_add_u32 s90, s60, 0x1000
	v_mov_b64_e32 v[0:1], 0
	v_mov_b64_e32 v[2:3], 0
	v_mov_b64_e32 v[4:5], 0
	v_mov_b64_e32 v[6:7], 0
	v_mov_b64_e32 v[8:9], 0
	v_mov_b64_e32 v[10:11], 0
	v_mov_b64_e32 v[12:13], 0
	v_mov_b64_e32 v[14:15], 0
	v_mov_b64_e32 v[16:17], 0
	v_mov_b64_e32 v[18:19], 0
	v_mov_b64_e32 v[20:21], 0
	v_mov_b64_e32 v[22:23], 0
	v_mov_b64_e32 v[24:25], 0
	v_mov_b64_e32 v[26:27], 0
	v_mov_b64_e32 v[28:29], 0
	v_mov_b64_e32 v[30:31], 0
	v_mov_b64_e32 v[32:33], 0
	v_mov_b64_e32 v[34:35], 0
	v_mov_b64_e32 v[36:37], 0
	v_mov_b64_e32 v[38:39], 0
	v_mov_b64_e32 v[40:41], 0
	v_mov_b64_e32 v[42:43], 0
	v_mov_b64_e32 v[44:45], 0
	v_mov_b64_e32 v[46:47], 0
	v_mov_b64_e32 v[48:49], 0
	v_mov_b64_e32 v[50:51], 0
	v_mov_b64_e32 v[68:69], 0
	v_mov_b64_e32 v[70:71], 0
	v_mov_b64_e32 v[88:89], 0
	v_mov_b64_e32 v[90:91], 0
	v_mov_b64_e32 v[92:93], 0
	v_mov_b64_e32 v[94:95], 0
	v_mov_b64_e32 v[96:97], 0
	v_mov_b64_e32 v[98:99], 0
	v_mov_b64_e32 v[100:101], 0
	v_mov_b64_e32 v[102:103], 0
	v_mov_b64_e32 v[104:105], 0
	v_mov_b64_e32 v[106:107], 0
	v_mov_b64_e32 v[108:109], 0
	v_mov_b64_e32 v[110:111], 0
	v_mov_b64_e32 v[112:113], 0
	v_mov_b64_e32 v[114:115], 0
	v_mov_b64_e32 v[116:117], 0
	v_mov_b64_e32 v[118:119], 0
	v_mov_b64_e32 v[120:121], 0
	v_mov_b64_e32 v[122:123], 0
	v_mov_b64_e32 v[124:125], 0
	v_mov_b64_e32 v[126:127], 0
	v_mov_b64_e32 v[128:129], 0
	v_mov_b64_e32 v[130:131], 0
	v_mov_b64_e32 v[132:133], 0
	v_mov_b64_e32 v[134:135], 0
	v_mov_b64_e32 v[136:137], 0
	v_mov_b64_e32 v[138:139], 0
	v_mov_b64_e32 v[140:141], 0
	v_mov_b64_e32 v[142:143], 0
	v_mov_b64_e32 v[144:145], 0
	v_mov_b64_e32 v[146:147], 0
	v_mov_b64_e32 v[148:149], 0
	v_mov_b64_e32 v[150:151], 0
	v_mov_b64_e32 v[152:153], 0
	v_mov_b64_e32 v[154:155], 0
	v_mov_b64_e32 v[156:157], 0
	v_mov_b64_e32 v[158:159], 0
	s_addc_u32 s91, s61, 0
	s_mov_b32 s93, -2

.LBB0_644:
	s_or_b64 exec, exec, s[10:11]
	s_waitcnt lgkmcnt(0)
	s_barrier
	v_cndmask_b32_e64 v182, 0, 1, s[38:39]
	s_nop 0
	v_cmp_ne_u32_e64 s[10:11], 1, v182
	s_and_b64 vcc, exec, s[38:39]
	s_cbranch_vccz .Lgu_cizero
	v_mbcnt_lo_u32_b32 v225, -1, 0
	v_mbcnt_hi_u32_b32 v225, -1, v225
	v_and_b32_e32 v225, 15, v225
	v_cmp_eq_u32_e32 vcc, 14, v225
	v_add_u32_e32 v225, 0x80, v185
	s_nop 0
	v_cndmask_b32_e32 v225, v225, v185, vcc
	ds_read_b128 v[208:211], v225
	ds_read_b128 v[212:215], v225 offset:16
	s_branch .LBB0_661
.Lgu_cizero:
	v_mov_b32_e32 v208, 0
	v_mov_b32_e32 v209, 0
	v_mov_b32_e32 v210, 0
	v_mov_b32_e32 v211, 0
	v_mov_b32_e32 v212, 0
	v_mov_b32_e32 v213, 0
	v_mov_b32_e32 v214, 0
	v_mov_b32_e32 v215, 0
.LBB0_661:
	s_waitcnt lgkmcnt(0)
	s_ashr_i32 s60, s12, 5
	s_ashr_i32 s61, s60, 31
	s_mov_b32 s100, 0xbfb8aa3b
	s_mov_b32 s101, 0xbfb8aa3b
	v_lshlrev_b32_e32 v252, 5, v181
	v_and_b32_e32 v252, 0x1e0, v252
	v_lshlrev_b32_e32 v252, 1, v252
	v_lshl_add_u32 v252, v170, 1, v252
	v_mov_b32_e32 v253, 0
	v_ashrrev_i32_e32 v225, 4, v181
	v_mov_b64_e32 v[234:235], s[60:61]
	v_mad_i64_i32 v[234:235], s[98:99], v225, s82, v[234:235]
	v_lshlrev_b64 v[234:235], 10, v[234:235]
	v_lshl_add_u64 v[234:235], s[36:37], 0, v[234:235]
	v_lshl_add_u64 v[234:235], v[234:235], 0, v[252:253]
	v_mov_b32_e32 v238, 0x56000
	v_mov_b32_e32 v239, 0
	v_fmamk_f32 v230, v168, 0x39800000, v191
	v_rsq_f32_e32 v230, v230
	v_and_b32_e32 v224, 0xfff, v181
	v_cmp_le_i32_e64 s[12:13], s53, v181
	v_cmp_gt_i32_e64 s[14:15], s73, v181
	v_cmp_gt_u32_e32 vcc, 2, v224
	v_pk_mul_f32 v[156:157], v[156:157], v[230:231] op_sel_hi:[1,0]
	v_pk_mul_f32 v[158:159], v[158:159], v[230:231] op_sel_hi:[1,0]
	v_pk_mul_f32 v[152:153], v[152:153], v[230:231] op_sel_hi:[1,0]
	v_pk_mul_f32 v[154:155], v[154:155], v[230:231] op_sel_hi:[1,0]
	v_pk_mul_f32 v[144:145], v[144:145], v[230:231] op_sel_hi:[1,0]
	v_pk_mul_f32 v[146:147], v[146:147], v[230:231] op_sel_hi:[1,0]
	v_pk_mul_f32 v[148:149], v[148:149], v[230:231] op_sel_hi:[1,0]
	v_pk_mul_f32 v[150:151], v[150:151], v[230:231] op_sel_hi:[1,0]
	s_cmp_eq_u64 vcc, 0
	s_cbranch_scc1 .Lgu_nss0
	v_cmp_eq_u32_e64 s[98:99], 0, v224
	s_nop 1
	v_cndmask_b32_e64 v56, v56, 0, vcc
	v_cndmask_b32_e64 v57, v57, 0, vcc
	v_cndmask_b32_e64 v58, v58, 0, vcc
	v_cndmask_b32_e64 v59, v59, 0, vcc
	v_cndmask_b32_e64 v76, v76, 0, vcc
	v_cndmask_b32_e64 v77, v77, 0, vcc
	v_cndmask_b32_e64 v78, v78, 0, vcc
	v_cndmask_b32_e64 v79, v79, 0, vcc
	v_cndmask_b32_e64 v60, v60, 0, s[98:99]
	v_cndmask_b32_e64 v61, v61, 0, s[98:99]
	v_cndmask_b32_e64 v62, v62, 0, s[98:99]
	v_cndmask_b32_e64 v63, v63, 0, s[98:99]
	v_cndmask_b32_e64 v80, v80, 0, s[98:99]
	v_cndmask_b32_e64 v81, v81, 0, s[98:99]
	v_cndmask_b32_e64 v82, v82, 0, s[98:99]
	v_cndmask_b32_e64 v83, v83, 0, s[98:99]
.Lgu_nss0:
	v_fma_f32 v244, v64, v156, v52
	v_fma_f32 v245, v65, v157, v53
	v_fma_f32 v246, v66, v158, v54
	v_fma_f32 v247, v67, v159, v55
	v_fma_f32 v248, v84, v152, v72
	v_fma_f32 v249, v85, v153, v73
	v_fma_f32 v250, v86, v154, v74
	v_fma_f32 v251, v87, v155, v75
	v_fmac_f32_dpp v244, v156, v56 row_shr:2 row_mask:0xf bank_mask:0xf bound_ctrl:0
	v_fmac_f32_dpp v245, v157, v57 row_shr:2 row_mask:0xf bank_mask:0xf bound_ctrl:0
	v_fmac_f32_dpp v246, v158, v58 row_shr:2 row_mask:0xf bank_mask:0xf bound_ctrl:0
	v_fmac_f32_dpp v247, v159, v59 row_shr:2 row_mask:0xf bank_mask:0xf bound_ctrl:0
	v_fmac_f32_dpp v248, v152, v76 row_shr:2 row_mask:0xf bank_mask:0xf bound_ctrl:0
	v_fmac_f32_dpp v249, v153, v77 row_shr:2 row_mask:0xf bank_mask:0xf bound_ctrl:0
	v_fmac_f32_dpp v250, v154, v78 row_shr:2 row_mask:0xf bank_mask:0xf bound_ctrl:0
	v_fmac_f32_dpp v251, v155, v79 row_shr:2 row_mask:0xf bank_mask:0xf bound_ctrl:0
	v_fmac_f32_dpp v244, v208, v56 row_shl:14 row_mask:0xf bank_mask:0xf bound_ctrl:0
	v_fmac_f32_dpp v245, v209, v57 row_shl:14 row_mask:0xf bank_mask:0xf bound_ctrl:0
	v_fmac_f32_dpp v246, v210, v58 row_shl:14 row_mask:0xf bank_mask:0xf bound_ctrl:0
	v_fmac_f32_dpp v247, v211, v59 row_shl:14 row_mask:0xf bank_mask:0xf bound_ctrl:0
	v_fmac_f32_dpp v248, v212, v76 row_shl:14 row_mask:0xf bank_mask:0xf bound_ctrl:0
	v_fmac_f32_dpp v249, v213, v77 row_shl:14 row_mask:0xf bank_mask:0xf bound_ctrl:0
	v_fmac_f32_dpp v250, v214, v78 row_shl:14 row_mask:0xf bank_mask:0xf bound_ctrl:0
	v_fmac_f32_dpp v251, v215, v79 row_shl:14 row_mask:0xf bank_mask:0xf bound_ctrl:0
	v_fmac_f32_dpp v244, v156, v60 row_shr:1 row_mask:0xf bank_mask:0xf bound_ctrl:0
	v_fmac_f32_dpp v245, v157, v61 row_shr:1 row_mask:0xf bank_mask:0xf bound_ctrl:0
	v_fmac_f32_dpp v246, v158, v62 row_shr:1 row_mask:0xf bank_mask:0xf bound_ctrl:0
	v_fmac_f32_dpp v247, v159, v63 row_shr:1 row_mask:0xf bank_mask:0xf bound_ctrl:0
	v_fmac_f32_dpp v248, v152, v80 row_shr:1 row_mask:0xf bank_mask:0xf bound_ctrl:0
	v_fmac_f32_dpp v249, v153, v81 row_shr:1 row_mask:0xf bank_mask:0xf bound_ctrl:0
	v_fmac_f32_dpp v250, v154, v82 row_shr:1 row_mask:0xf bank_mask:0xf bound_ctrl:0
	v_fmac_f32_dpp v251, v155, v83 row_shr:1 row_mask:0xf bank_mask:0xf bound_ctrl:0
	v_fmac_f32_dpp v244, v208, v60 row_shl:15 row_mask:0xf bank_mask:0xf bound_ctrl:0
	v_fmac_f32_dpp v245, v209, v61 row_shl:15 row_mask:0xf bank_mask:0xf bound_ctrl:0
	v_fmac_f32_dpp v246, v210, v62 row_shl:15 row_mask:0xf bank_mask:0xf bound_ctrl:0
	v_fmac_f32_dpp v247, v211, v63 row_shl:15 row_mask:0xf bank_mask:0xf bound_ctrl:0
	v_fmac_f32_dpp v248, v212, v80 row_shl:15 row_mask:0xf bank_mask:0xf bound_ctrl:0
	v_fmac_f32_dpp v249, v213, v81 row_shl:15 row_mask:0xf bank_mask:0xf bound_ctrl:0
	v_fmac_f32_dpp v250, v214, v82 row_shl:15 row_mask:0xf bank_mask:0xf bound_ctrl:0
	v_fmac_f32_dpp v251, v215, v83 row_shl:15 row_mask:0xf bank_mask:0xf bound_ctrl:0
	v_pk_mul_f32 v[216:217], v[244:245], s[100:101]
	v_pk_mul_f32 v[218:219], v[246:247], s[100:101]
	v_pk_mul_f32 v[220:221], v[248:249], s[100:101]
	v_pk_mul_f32 v[222:223], v[250:251], s[100:101]
	v_exp_f32_e32 v216, v216
	v_exp_f32_e32 v217, v217
	v_exp_f32_e32 v218, v218
	v_exp_f32_e32 v219, v219
	v_exp_f32_e32 v220, v220
	v_exp_f32_e32 v221, v221
	v_exp_f32_e32 v222, v222
	v_exp_f32_e32 v223, v223
	v_pk_add_f32 v[216:217], v[216:217], 1.0 op_sel_hi:[1,0]
	v_pk_add_f32 v[218:219], v[218:219], 1.0 op_sel_hi:[1,0]
	v_pk_add_f32 v[220:221], v[220:221], 1.0 op_sel_hi:[1,0]
	v_pk_add_f32 v[222:223], v[222:223], 1.0 op_sel_hi:[1,0]
	v_rcp_f32_e32 v216, v216
	v_rcp_f32_e32 v217, v217
	v_rcp_f32_e32 v218, v218
	v_rcp_f32_e32 v219, v219
	v_rcp_f32_e32 v220, v220
	v_rcp_f32_e32 v221, v221
	v_rcp_f32_e32 v222, v222
	v_rcp_f32_e32 v223, v223
	v_pk_mul_f32 v[244:245], v[244:245], v[216:217]
	v_pk_mul_f32 v[246:247], v[246:247], v[218:219]
	v_pk_mul_f32 v[248:249], v[248:249], v[220:221]
	v_pk_mul_f32 v[250:251], v[250:251], v[222:223]
	v_pk_mul_f32 v[244:245], v[144:145], v[244:245]
	v_pk_mul_f32 v[246:247], v[146:147], v[246:247]
	v_pk_mul_f32 v[248:249], v[148:149], v[248:249]
	v_pk_mul_f32 v[250:251], v[150:151], v[250:251]
	v_cvt_pk_bf16_f32 v240, v244, v245
	v_cvt_pk_bf16_f32 v241, v246, v247
	v_cvt_pk_bf16_f32 v242, v248, v249
	v_cvt_pk_bf16_f32 v243, v250, v251
	s_and_b64 s[12:13], s[12:13], s[14:15]
	s_and_saveexec_b64 s[62:63], s[12:13]
	global_store_dwordx4 v[234:235], v[240:243], off
	s_or_b64 exec, exec, s[62:63]
	s_cmp_eq_u64 vcc, 0
	s_cbranch_scc1 .Lgu_nrl0
	global_load_dwordx4 v[76:79], v229, s[50:51] offset:16
	global_load_dwordx4 v[56:59], v229, s[50:51]
	global_load_dwordx4 v[80:83], v229, s[46:47] offset:16
	global_load_dwordx4 v[60:63], v229, s[46:47]
	s_waitcnt vmcnt(0)

.Lgu_nss1:
	v_fma_f32 v244, v64, v140, v52
	v_fma_f32 v245, v65, v141, v53
	v_fma_f32 v246, v66, v142, v54
	v_fma_f32 v247, v67, v143, v55
	v_fma_f32 v248, v84, v136, v72
	v_fma_f32 v249, v85, v137, v73
	v_fma_f32 v250, v86, v138, v74
	v_fma_f32 v251, v87, v139, v75
	v_fmac_f32_dpp v244, v140, v56 row_shr:2 row_mask:0xf bank_mask:0xf bound_ctrl:0
	v_fmac_f32_dpp v245, v141, v57 row_shr:2 row_mask:0xf bank_mask:0xf bound_ctrl:0
	v_fmac_f32_dpp v246, v142, v58 row_shr:2 row_mask:0xf bank_mask:0xf bound_ctrl:0
	v_fmac_f32_dpp v247, v143, v59 row_shr:2 row_mask:0xf bank_mask:0xf bound_ctrl:0
	v_fmac_f32_dpp v248, v136, v76 row_shr:2 row_mask:0xf bank_mask:0xf bound_ctrl:0
	v_fmac_f32_dpp v249, v137, v77 row_shr:2 row_mask:0xf bank_mask:0xf bound_ctrl:0
	v_fmac_f32_dpp v250, v138, v78 row_shr:2 row_mask:0xf bank_mask:0xf bound_ctrl:0
	v_fmac_f32_dpp v251, v139, v79 row_shr:2 row_mask:0xf bank_mask:0xf bound_ctrl:0
	v_fmac_f32_dpp v244, v156, v56 row_shl:14 row_mask:0xf bank_mask:0xf bound_ctrl:0
	v_fmac_f32_dpp v245, v157, v57 row_shl:14 row_mask:0xf bank_mask:0xf bound_ctrl:0
	v_fmac_f32_dpp v246, v158, v58 row_shl:14 row_mask:0xf bank_mask:0xf bound_ctrl:0
	v_fmac_f32_dpp v247, v159, v59 row_shl:14 row_mask:0xf bank_mask:0xf bound_ctrl:0
	v_fmac_f32_dpp v248, v152, v76 row_shl:14 row_mask:0xf bank_mask:0xf bound_ctrl:0
	v_fmac_f32_dpp v249, v153, v77 row_shl:14 row_mask:0xf bank_mask:0xf bound_ctrl:0
	v_fmac_f32_dpp v250, v154, v78 row_shl:14 row_mask:0xf bank_mask:0xf bound_ctrl:0
	v_fmac_f32_dpp v251, v155, v79 row_shl:14 row_mask:0xf bank_mask:0xf bound_ctrl:0
	v_fmac_f32_dpp v244, v140, v60 row_shr:1 row_mask:0xf bank_mask:0xf bound_ctrl:0
	v_fmac_f32_dpp v245, v141, v61 row_shr:1 row_mask:0xf bank_mask:0xf bound_ctrl:0
	v_fmac_f32_dpp v246, v142, v62 row_shr:1 row_mask:0xf bank_mask:0xf bound_ctrl:0
	v_fmac_f32_dpp v247, v143, v63 row_shr:1 row_mask:0xf bank_mask:0xf bound_ctrl:0
	v_fmac_f32_dpp v248, v136, v80 row_shr:1 row_mask:0xf bank_mask:0xf bound_ctrl:0
	v_fmac_f32_dpp v249, v137, v81 row_shr:1 row_mask:0xf bank_mask:0xf bound_ctrl:0
	v_fmac_f32_dpp v250, v138, v82 row_shr:1 row_mask:0xf bank_mask:0xf bound_ctrl:0
	v_fmac_f32_dpp v251, v139, v83 row_shr:1 row_mask:0xf bank_mask:0xf bound_ctrl:0
	v_fmac_f32_dpp v244, v156, v60 row_shl:15 row_mask:0xf bank_mask:0xf bound_ctrl:0
	v_fmac_f32_dpp v245, v157, v61 row_shl:15 row_mask:0xf bank_mask:0xf bound_ctrl:0
	v_fmac_f32_dpp v246, v158, v62 row_shl:15 row_mask:0xf bank_mask:0xf bound_ctrl:0
	v_fmac_f32_dpp v247, v159, v63 row_shl:15 row_mask:0xf bank_mask:0xf bound_ctrl:0
	v_fmac_f32_dpp v248, v152, v80 row_shl:15 row_mask:0xf bank_mask:0xf bound_ctrl:0
	v_fmac_f32_dpp v249, v153, v81 row_shl:15 row_mask:0xf bank_mask:0xf bound_ctrl:0
	v_fmac_f32_dpp v250, v154, v82 row_shl:15 row_mask:0xf bank_mask:0xf bound_ctrl:0
	v_fmac_f32_dpp v251, v155, v83 row_shl:15 row_mask:0xf bank_mask:0xf bound_ctrl:0
	v_pk_mul_f32 v[216:217], v[244:245], s[100:101]
	v_pk_mul_f32 v[218:219], v[246:247], s[100:101]
	v_pk_mul_f32 v[220:221], v[248:249], s[100:101]
	v_pk_mul_f32 v[222:223], v[250:251], s[100:101]
	v_exp_f32_e32 v216, v216
	v_exp_f32_e32 v217, v217
	v_exp_f32_e32 v218, v218
	v_exp_f32_e32 v219, v219
	v_exp_f32_e32 v220, v220
	v_exp_f32_e32 v221, v221
	v_exp_f32_e32 v222, v222
	v_exp_f32_e32 v223, v223
	v_pk_add_f32 v[216:217], v[216:217], 1.0 op_sel_hi:[1,0]
	v_pk_add_f32 v[218:219], v[218:219], 1.0 op_sel_hi:[1,0]
	v_pk_add_f32 v[220:221], v[220:221], 1.0 op_sel_hi:[1,0]
	v_pk_add_f32 v[222:223], v[222:223], 1.0 op_sel_hi:[1,0]
	v_rcp_f32_e32 v216, v216
	v_rcp_f32_e32 v217, v217
	v_rcp_f32_e32 v218, v218
	v_rcp_f32_e32 v219, v219
	v_rcp_f32_e32 v220, v220
	v_rcp_f32_e32 v221, v221
	v_rcp_f32_e32 v222, v222
	v_rcp_f32_e32 v223, v223
	v_pk_mul_f32 v[244:245], v[244:245], v[216:217]
	v_pk_mul_f32 v[246:247], v[246:247], v[218:219]
	v_pk_mul_f32 v[248:249], v[248:249], v[220:221]
	v_pk_mul_f32 v[250:251], v[250:251], v[222:223]
	v_pk_mul_f32 v[244:245], v[128:129], v[244:245]
	v_pk_mul_f32 v[246:247], v[130:131], v[246:247]
	v_pk_mul_f32 v[248:249], v[132:133], v[248:249]
	v_pk_mul_f32 v[250:251], v[134:135], v[250:251]
	v_cvt_pk_bf16_f32 v240, v244, v245
	v_cvt_pk_bf16_f32 v241, v246, v247
	v_cvt_pk_bf16_f32 v242, v248, v249
	v_cvt_pk_bf16_f32 v243, v250, v251
	v_lshl_add_u64 v[234:235], v[234:235], 0, v[238:239]
	s_and_b64 s[12:13], s[12:13], s[14:15]
	s_and_saveexec_b64 s[62:63], s[12:13]
	global_store_dwordx4 v[234:235], v[240:243], off
	s_or_b64 exec, exec, s[62:63]
	s_cmp_eq_u64 vcc, 0
	s_cbranch_scc1 .Lgu_nrl1
	global_load_dwordx4 v[76:79], v229, s[50:51] offset:16
	global_load_dwordx4 v[56:59], v229, s[50:51]
	global_load_dwordx4 v[80:83], v229, s[46:47] offset:16
	global_load_dwordx4 v[60:63], v229, s[46:47]
	s_waitcnt vmcnt(0)

.Lgu_nss2:
	v_fma_f32 v244, v64, v124, v52
	v_fma_f32 v245, v65, v125, v53
	v_fma_f32 v246, v66, v126, v54
	v_fma_f32 v247, v67, v127, v55
	v_fma_f32 v248, v84, v120, v72
	v_fma_f32 v249, v85, v121, v73
	v_fma_f32 v250, v86, v122, v74
	v_fma_f32 v251, v87, v123, v75
	v_fmac_f32_dpp v244, v124, v56 row_shr:2 row_mask:0xf bank_mask:0xf bound_ctrl:0
	v_fmac_f32_dpp v245, v125, v57 row_shr:2 row_mask:0xf bank_mask:0xf bound_ctrl:0
	v_fmac_f32_dpp v246, v126, v58 row_shr:2 row_mask:0xf bank_mask:0xf bound_ctrl:0
	v_fmac_f32_dpp v247, v127, v59 row_shr:2 row_mask:0xf bank_mask:0xf bound_ctrl:0
	v_fmac_f32_dpp v248, v120, v76 row_shr:2 row_mask:0xf bank_mask:0xf bound_ctrl:0
	v_fmac_f32_dpp v249, v121, v77 row_shr:2 row_mask:0xf bank_mask:0xf bound_ctrl:0
	v_fmac_f32_dpp v250, v122, v78 row_shr:2 row_mask:0xf bank_mask:0xf bound_ctrl:0
	v_fmac_f32_dpp v251, v123, v79 row_shr:2 row_mask:0xf bank_mask:0xf bound_ctrl:0
	v_fmac_f32_dpp v244, v140, v56 row_shl:14 row_mask:0xf bank_mask:0xf bound_ctrl:0
	v_fmac_f32_dpp v245, v141, v57 row_shl:14 row_mask:0xf bank_mask:0xf bound_ctrl:0
	v_fmac_f32_dpp v246, v142, v58 row_shl:14 row_mask:0xf bank_mask:0xf bound_ctrl:0
	v_fmac_f32_dpp v247, v143, v59 row_shl:14 row_mask:0xf bank_mask:0xf bound_ctrl:0
	v_fmac_f32_dpp v248, v136, v76 row_shl:14 row_mask:0xf bank_mask:0xf bound_ctrl:0
	v_fmac_f32_dpp v249, v137, v77 row_shl:14 row_mask:0xf bank_mask:0xf bound_ctrl:0
	v_fmac_f32_dpp v250, v138, v78 row_shl:14 row_mask:0xf bank_mask:0xf bound_ctrl:0
	v_fmac_f32_dpp v251, v139, v79 row_shl:14 row_mask:0xf bank_mask:0xf bound_ctrl:0
	v_fmac_f32_dpp v244, v124, v60 row_shr:1 row_mask:0xf bank_mask:0xf bound_ctrl:0
	v_fmac_f32_dpp v245, v125, v61 row_shr:1 row_mask:0xf bank_mask:0xf bound_ctrl:0
	v_fmac_f32_dpp v246, v126, v62 row_shr:1 row_mask:0xf bank_mask:0xf bound_ctrl:0
	v_fmac_f32_dpp v247, v127, v63 row_shr:1 row_mask:0xf bank_mask:0xf bound_ctrl:0
	v_fmac_f32_dpp v248, v120, v80 row_shr:1 row_mask:0xf bank_mask:0xf bound_ctrl:0
	v_fmac_f32_dpp v249, v121, v81 row_shr:1 row_mask:0xf bank_mask:0xf bound_ctrl:0
	v_fmac_f32_dpp v250, v122, v82 row_shr:1 row_mask:0xf bank_mask:0xf bound_ctrl:0
	v_fmac_f32_dpp v251, v123, v83 row_shr:1 row_mask:0xf bank_mask:0xf bound_ctrl:0
	v_fmac_f32_dpp v244, v140, v60 row_shl:15 row_mask:0xf bank_mask:0xf bound_ctrl:0
	v_fmac_f32_dpp v245, v141, v61 row_shl:15 row_mask:0xf bank_mask:0xf bound_ctrl:0
	v_fmac_f32_dpp v246, v142, v62 row_shl:15 row_mask:0xf bank_mask:0xf bound_ctrl:0
	v_fmac_f32_dpp v247, v143, v63 row_shl:15 row_mask:0xf bank_mask:0xf bound_ctrl:0
	v_fmac_f32_dpp v248, v136, v80 row_shl:15 row_mask:0xf bank_mask:0xf bound_ctrl:0
	v_fmac_f32_dpp v249, v137, v81 row_shl:15 row_mask:0xf bank_mask:0xf bound_ctrl:0
	v_fmac_f32_dpp v250, v138, v82 row_shl:15 row_mask:0xf bank_mask:0xf bound_ctrl:0
	v_fmac_f32_dpp v251, v139, v83 row_shl:15 row_mask:0xf bank_mask:0xf bound_ctrl:0
	v_pk_mul_f32 v[216:217], v[244:245], s[100:101]
	v_pk_mul_f32 v[218:219], v[246:247], s[100:101]
	v_pk_mul_f32 v[220:221], v[248:249], s[100:101]
	v_pk_mul_f32 v[222:223], v[250:251], s[100:101]
	v_exp_f32_e32 v216, v216
	v_exp_f32_e32 v217, v217
	v_exp_f32_e32 v218, v218
	v_exp_f32_e32 v219, v219
	v_exp_f32_e32 v220, v220
	v_exp_f32_e32 v221, v221
	v_exp_f32_e32 v222, v222
	v_exp_f32_e32 v223, v223
	v_pk_add_f32 v[216:217], v[216:217], 1.0 op_sel_hi:[1,0]
	v_pk_add_f32 v[218:219], v[218:219], 1.0 op_sel_hi:[1,0]
	v_pk_add_f32 v[220:221], v[220:221], 1.0 op_sel_hi:[1,0]
	v_pk_add_f32 v[222:223], v[222:223], 1.0 op_sel_hi:[1,0]
	v_rcp_f32_e32 v216, v216
	v_rcp_f32_e32 v217, v217
	v_rcp_f32_e32 v218, v218
	v_rcp_f32_e32 v219, v219
	v_rcp_f32_e32 v220, v220
	v_rcp_f32_e32 v221, v221
	v_rcp_f32_e32 v222, v222
	v_rcp_f32_e32 v223, v223
	v_pk_mul_f32 v[244:245], v[244:245], v[216:217]
	v_pk_mul_f32 v[246:247], v[246:247], v[218:219]
	v_pk_mul_f32 v[248:249], v[248:249], v[220:221]
	v_pk_mul_f32 v[250:251], v[250:251], v[222:223]
	v_pk_mul_f32 v[244:245], v[112:113], v[244:245]
	v_pk_mul_f32 v[246:247], v[114:115], v[246:247]
	v_pk_mul_f32 v[248:249], v[116:117], v[248:249]
	v_pk_mul_f32 v[250:251], v[118:119], v[250:251]
	v_cvt_pk_bf16_f32 v240, v244, v245
	v_cvt_pk_bf16_f32 v241, v246, v247
	v_cvt_pk_bf16_f32 v242, v248, v249
	v_cvt_pk_bf16_f32 v243, v250, v251
	v_lshl_add_u64 v[234:235], v[234:235], 0, v[238:239]
	s_and_b64 s[12:13], s[12:13], s[14:15]
	s_and_saveexec_b64 s[62:63], s[12:13]
	global_store_dwordx4 v[234:235], v[240:243], off
	s_or_b64 exec, exec, s[62:63]
	s_cmp_eq_u64 vcc, 0
	s_cbranch_scc1 .Lgu_nrl2
	global_load_dwordx4 v[76:79], v229, s[50:51] offset:16
	global_load_dwordx4 v[56:59], v229, s[50:51]
	global_load_dwordx4 v[80:83], v229, s[46:47] offset:16
	global_load_dwordx4 v[60:63], v229, s[46:47]
	s_waitcnt vmcnt(0)

.Lgu_nss3:
	v_fma_f32 v244, v64, v108, v52
	v_fma_f32 v245, v65, v109, v53
	v_fma_f32 v246, v66, v110, v54
	v_fma_f32 v247, v67, v111, v55
	v_fma_f32 v248, v84, v104, v72
	v_fma_f32 v249, v85, v105, v73
	v_fma_f32 v250, v86, v106, v74
	v_fma_f32 v251, v87, v107, v75
	v_fmac_f32_dpp v244, v108, v56 row_shr:2 row_mask:0xf bank_mask:0xf bound_ctrl:0
	v_fmac_f32_dpp v245, v109, v57 row_shr:2 row_mask:0xf bank_mask:0xf bound_ctrl:0
	v_fmac_f32_dpp v246, v110, v58 row_shr:2 row_mask:0xf bank_mask:0xf bound_ctrl:0
	v_fmac_f32_dpp v247, v111, v59 row_shr:2 row_mask:0xf bank_mask:0xf bound_ctrl:0
	v_fmac_f32_dpp v248, v104, v76 row_shr:2 row_mask:0xf bank_mask:0xf bound_ctrl:0
	v_fmac_f32_dpp v249, v105, v77 row_shr:2 row_mask:0xf bank_mask:0xf bound_ctrl:0
	v_fmac_f32_dpp v250, v106, v78 row_shr:2 row_mask:0xf bank_mask:0xf bound_ctrl:0
	v_fmac_f32_dpp v251, v107, v79 row_shr:2 row_mask:0xf bank_mask:0xf bound_ctrl:0
	v_fmac_f32_dpp v244, v124, v56 row_shl:14 row_mask:0xf bank_mask:0xf bound_ctrl:0
	v_fmac_f32_dpp v245, v125, v57 row_shl:14 row_mask:0xf bank_mask:0xf bound_ctrl:0
	v_fmac_f32_dpp v246, v126, v58 row_shl:14 row_mask:0xf bank_mask:0xf bound_ctrl:0
	v_fmac_f32_dpp v247, v127, v59 row_shl:14 row_mask:0xf bank_mask:0xf bound_ctrl:0
	v_fmac_f32_dpp v248, v120, v76 row_shl:14 row_mask:0xf bank_mask:0xf bound_ctrl:0
	v_fmac_f32_dpp v249, v121, v77 row_shl:14 row_mask:0xf bank_mask:0xf bound_ctrl:0
	v_fmac_f32_dpp v250, v122, v78 row_shl:14 row_mask:0xf bank_mask:0xf bound_ctrl:0
	v_fmac_f32_dpp v251, v123, v79 row_shl:14 row_mask:0xf bank_mask:0xf bound_ctrl:0
	v_fmac_f32_dpp v244, v108, v60 row_shr:1 row_mask:0xf bank_mask:0xf bound_ctrl:0
	v_fmac_f32_dpp v245, v109, v61 row_shr:1 row_mask:0xf bank_mask:0xf bound_ctrl:0
	v_fmac_f32_dpp v246, v110, v62 row_shr:1 row_mask:0xf bank_mask:0xf bound_ctrl:0
	v_fmac_f32_dpp v247, v111, v63 row_shr:1 row_mask:0xf bank_mask:0xf bound_ctrl:0
	v_fmac_f32_dpp v248, v104, v80 row_shr:1 row_mask:0xf bank_mask:0xf bound_ctrl:0
	v_fmac_f32_dpp v249, v105, v81 row_shr:1 row_mask:0xf bank_mask:0xf bound_ctrl:0
	v_fmac_f32_dpp v250, v106, v82 row_shr:1 row_mask:0xf bank_mask:0xf bound_ctrl:0
	v_fmac_f32_dpp v251, v107, v83 row_shr:1 row_mask:0xf bank_mask:0xf bound_ctrl:0
	v_fmac_f32_dpp v244, v124, v60 row_shl:15 row_mask:0xf bank_mask:0xf bound_ctrl:0
	v_fmac_f32_dpp v245, v125, v61 row_shl:15 row_mask:0xf bank_mask:0xf bound_ctrl:0
	v_fmac_f32_dpp v246, v126, v62 row_shl:15 row_mask:0xf bank_mask:0xf bound_ctrl:0
	v_fmac_f32_dpp v247, v127, v63 row_shl:15 row_mask:0xf bank_mask:0xf bound_ctrl:0
	v_fmac_f32_dpp v248, v120, v80 row_shl:15 row_mask:0xf bank_mask:0xf bound_ctrl:0
	v_fmac_f32_dpp v249, v121, v81 row_shl:15 row_mask:0xf bank_mask:0xf bound_ctrl:0
	v_fmac_f32_dpp v250, v122, v82 row_shl:15 row_mask:0xf bank_mask:0xf bound_ctrl:0
	v_fmac_f32_dpp v251, v123, v83 row_shl:15 row_mask:0xf bank_mask:0xf bound_ctrl:0
	v_pk_mul_f32 v[216:217], v[244:245], s[100:101]
	v_pk_mul_f32 v[218:219], v[246:247], s[100:101]
	v_pk_mul_f32 v[220:221], v[248:249], s[100:101]
	v_pk_mul_f32 v[222:223], v[250:251], s[100:101]
	v_exp_f32_e32 v216, v216
	v_exp_f32_e32 v217, v217
	v_exp_f32_e32 v218, v218
	v_exp_f32_e32 v219, v219
	v_exp_f32_e32 v220, v220
	v_exp_f32_e32 v221, v221
	v_exp_f32_e32 v222, v222
	v_exp_f32_e32 v223, v223
	v_pk_add_f32 v[216:217], v[216:217], 1.0 op_sel_hi:[1,0]
	v_pk_add_f32 v[218:219], v[218:219], 1.0 op_sel_hi:[1,0]
	v_pk_add_f32 v[220:221], v[220:221], 1.0 op_sel_hi:[1,0]
	v_pk_add_f32 v[222:223], v[222:223], 1.0 op_sel_hi:[1,0]
	v_rcp_f32_e32 v216, v216
	v_rcp_f32_e32 v217, v217
	v_rcp_f32_e32 v218, v218
	v_rcp_f32_e32 v219, v219
	v_rcp_f32_e32 v220, v220
	v_rcp_f32_e32 v221, v221
	v_rcp_f32_e32 v222, v222
	v_rcp_f32_e32 v223, v223
	v_pk_mul_f32 v[244:245], v[244:245], v[216:217]
	v_pk_mul_f32 v[246:247], v[246:247], v[218:219]
	v_pk_mul_f32 v[248:249], v[248:249], v[220:221]
	v_pk_mul_f32 v[250:251], v[250:251], v[222:223]
	v_pk_mul_f32 v[244:245], v[96:97], v[244:245]
	v_pk_mul_f32 v[246:247], v[98:99], v[246:247]
	v_pk_mul_f32 v[248:249], v[100:101], v[248:249]
	v_pk_mul_f32 v[250:251], v[102:103], v[250:251]
	v_cvt_pk_bf16_f32 v240, v244, v245
	v_cvt_pk_bf16_f32 v241, v246, v247
	v_cvt_pk_bf16_f32 v242, v248, v249
	v_cvt_pk_bf16_f32 v243, v250, v251
	v_lshl_add_u64 v[234:235], v[234:235], 0, v[238:239]
	s_and_b64 s[12:13], s[12:13], s[14:15]
	s_and_saveexec_b64 s[62:63], s[12:13]
	global_store_dwordx4 v[234:235], v[240:243], off
	s_or_b64 exec, exec, s[62:63]
	s_cmp_eq_u64 vcc, 0
	s_cbranch_scc1 .Lgu_nrl3
	global_load_dwordx4 v[76:79], v229, s[50:51] offset:16
	global_load_dwordx4 v[56:59], v229, s[50:51]
	global_load_dwordx4 v[80:83], v229, s[46:47] offset:16
	global_load_dwordx4 v[60:63], v229, s[46:47]
	s_waitcnt vmcnt(0)

.Lgu_nss4:
	v_fma_f32 v244, v64, v92, v52
	v_fma_f32 v245, v65, v93, v53
	v_fma_f32 v246, v66, v94, v54
	v_fma_f32 v247, v67, v95, v55
	v_fma_f32 v248, v84, v88, v72
	v_fma_f32 v249, v85, v89, v73
	v_fma_f32 v250, v86, v90, v74
	v_fma_f32 v251, v87, v91, v75
	v_fmac_f32_dpp v244, v92, v56 row_shr:2 row_mask:0xf bank_mask:0xf bound_ctrl:0
	v_fmac_f32_dpp v245, v93, v57 row_shr:2 row_mask:0xf bank_mask:0xf bound_ctrl:0
	v_fmac_f32_dpp v246, v94, v58 row_shr:2 row_mask:0xf bank_mask:0xf bound_ctrl:0
	v_fmac_f32_dpp v247, v95, v59 row_shr:2 row_mask:0xf bank_mask:0xf bound_ctrl:0
	v_fmac_f32_dpp v248, v88, v76 row_shr:2 row_mask:0xf bank_mask:0xf bound_ctrl:0
	v_fmac_f32_dpp v249, v89, v77 row_shr:2 row_mask:0xf bank_mask:0xf bound_ctrl:0
	v_fmac_f32_dpp v250, v90, v78 row_shr:2 row_mask:0xf bank_mask:0xf bound_ctrl:0
	v_fmac_f32_dpp v251, v91, v79 row_shr:2 row_mask:0xf bank_mask:0xf bound_ctrl:0
	v_fmac_f32_dpp v244, v108, v56 row_shl:14 row_mask:0xf bank_mask:0xf bound_ctrl:0
	v_fmac_f32_dpp v245, v109, v57 row_shl:14 row_mask:0xf bank_mask:0xf bound_ctrl:0
	v_fmac_f32_dpp v246, v110, v58 row_shl:14 row_mask:0xf bank_mask:0xf bound_ctrl:0
	v_fmac_f32_dpp v247, v111, v59 row_shl:14 row_mask:0xf bank_mask:0xf bound_ctrl:0
	v_fmac_f32_dpp v248, v104, v76 row_shl:14 row_mask:0xf bank_mask:0xf bound_ctrl:0
	v_fmac_f32_dpp v249, v105, v77 row_shl:14 row_mask:0xf bank_mask:0xf bound_ctrl:0
	v_fmac_f32_dpp v250, v106, v78 row_shl:14 row_mask:0xf bank_mask:0xf bound_ctrl:0
	v_fmac_f32_dpp v251, v107, v79 row_shl:14 row_mask:0xf bank_mask:0xf bound_ctrl:0
	v_fmac_f32_dpp v244, v92, v60 row_shr:1 row_mask:0xf bank_mask:0xf bound_ctrl:0
	v_fmac_f32_dpp v245, v93, v61 row_shr:1 row_mask:0xf bank_mask:0xf bound_ctrl:0
	v_fmac_f32_dpp v246, v94, v62 row_shr:1 row_mask:0xf bank_mask:0xf bound_ctrl:0
	v_fmac_f32_dpp v247, v95, v63 row_shr:1 row_mask:0xf bank_mask:0xf bound_ctrl:0
	v_fmac_f32_dpp v248, v88, v80 row_shr:1 row_mask:0xf bank_mask:0xf bound_ctrl:0
	v_fmac_f32_dpp v249, v89, v81 row_shr:1 row_mask:0xf bank_mask:0xf bound_ctrl:0
	v_fmac_f32_dpp v250, v90, v82 row_shr:1 row_mask:0xf bank_mask:0xf bound_ctrl:0
	v_fmac_f32_dpp v251, v91, v83 row_shr:1 row_mask:0xf bank_mask:0xf bound_ctrl:0
	v_fmac_f32_dpp v244, v108, v60 row_shl:15 row_mask:0xf bank_mask:0xf bound_ctrl:0
	v_fmac_f32_dpp v245, v109, v61 row_shl:15 row_mask:0xf bank_mask:0xf bound_ctrl:0
	v_fmac_f32_dpp v246, v110, v62 row_shl:15 row_mask:0xf bank_mask:0xf bound_ctrl:0
	v_fmac_f32_dpp v247, v111, v63 row_shl:15 row_mask:0xf bank_mask:0xf bound_ctrl:0
	v_fmac_f32_dpp v248, v104, v80 row_shl:15 row_mask:0xf bank_mask:0xf bound_ctrl:0
	v_fmac_f32_dpp v249, v105, v81 row_shl:15 row_mask:0xf bank_mask:0xf bound_ctrl:0
	v_fmac_f32_dpp v250, v106, v82 row_shl:15 row_mask:0xf bank_mask:0xf bound_ctrl:0
	v_fmac_f32_dpp v251, v107, v83 row_shl:15 row_mask:0xf bank_mask:0xf bound_ctrl:0
	v_pk_mul_f32 v[216:217], v[244:245], s[100:101]
	v_pk_mul_f32 v[218:219], v[246:247], s[100:101]
	v_pk_mul_f32 v[220:221], v[248:249], s[100:101]
	v_pk_mul_f32 v[222:223], v[250:251], s[100:101]
	v_exp_f32_e32 v216, v216
	v_exp_f32_e32 v217, v217
	v_exp_f32_e32 v218, v218
	v_exp_f32_e32 v219, v219
	v_exp_f32_e32 v220, v220
	v_exp_f32_e32 v221, v221
	v_exp_f32_e32 v222, v222
	v_exp_f32_e32 v223, v223
	v_pk_add_f32 v[216:217], v[216:217], 1.0 op_sel_hi:[1,0]
	v_pk_add_f32 v[218:219], v[218:219], 1.0 op_sel_hi:[1,0]
	v_pk_add_f32 v[220:221], v[220:221], 1.0 op_sel_hi:[1,0]
	v_pk_add_f32 v[222:223], v[222:223], 1.0 op_sel_hi:[1,0]
	v_rcp_f32_e32 v216, v216
	v_rcp_f32_e32 v217, v217
	v_rcp_f32_e32 v218, v218
	v_rcp_f32_e32 v219, v219
	v_rcp_f32_e32 v220, v220
	v_rcp_f32_e32 v221, v221
	v_rcp_f32_e32 v222, v222
	v_rcp_f32_e32 v223, v223
	v_pk_mul_f32 v[244:245], v[244:245], v[216:217]
	v_pk_mul_f32 v[246:247], v[246:247], v[218:219]
	v_pk_mul_f32 v[248:249], v[248:249], v[220:221]
	v_pk_mul_f32 v[250:251], v[250:251], v[222:223]
	v_pk_mul_f32 v[244:245], v[48:49], v[244:245]
	v_pk_mul_f32 v[246:247], v[50:51], v[246:247]
	v_pk_mul_f32 v[248:249], v[68:69], v[248:249]
	v_pk_mul_f32 v[250:251], v[70:71], v[250:251]
	v_cvt_pk_bf16_f32 v240, v244, v245
	v_cvt_pk_bf16_f32 v241, v246, v247
	v_cvt_pk_bf16_f32 v242, v248, v249
	v_cvt_pk_bf16_f32 v243, v250, v251
	v_lshl_add_u64 v[234:235], v[234:235], 0, v[238:239]
	s_and_b64 s[12:13], s[12:13], s[14:15]
	s_and_saveexec_b64 s[62:63], s[12:13]
	global_store_dwordx4 v[234:235], v[240:243], off
	s_or_b64 exec, exec, s[62:63]
	s_cmp_eq_u64 vcc, 0
	s_cbranch_scc1 .Lgu_nrl4
	global_load_dwordx4 v[76:79], v229, s[50:51] offset:16
	global_load_dwordx4 v[56:59], v229, s[50:51]
	global_load_dwordx4 v[80:83], v229, s[46:47] offset:16
	global_load_dwordx4 v[60:63], v229, s[46:47]
	s_waitcnt vmcnt(0)

.Lgu_nss5:
	v_fma_f32 v244, v64, v44, v52
	v_fma_f32 v245, v65, v45, v53
	v_fma_f32 v246, v66, v46, v54
	v_fma_f32 v247, v67, v47, v55
	v_fma_f32 v248, v84, v40, v72
	v_fma_f32 v249, v85, v41, v73
	v_fma_f32 v250, v86, v42, v74
	v_fma_f32 v251, v87, v43, v75
	v_fmac_f32_dpp v244, v44, v56 row_shr:2 row_mask:0xf bank_mask:0xf bound_ctrl:0
	v_fmac_f32_dpp v245, v45, v57 row_shr:2 row_mask:0xf bank_mask:0xf bound_ctrl:0
	v_fmac_f32_dpp v246, v46, v58 row_shr:2 row_mask:0xf bank_mask:0xf bound_ctrl:0
	v_fmac_f32_dpp v247, v47, v59 row_shr:2 row_mask:0xf bank_mask:0xf bound_ctrl:0
	v_fmac_f32_dpp v248, v40, v76 row_shr:2 row_mask:0xf bank_mask:0xf bound_ctrl:0
	v_fmac_f32_dpp v249, v41, v77 row_shr:2 row_mask:0xf bank_mask:0xf bound_ctrl:0
	v_fmac_f32_dpp v250, v42, v78 row_shr:2 row_mask:0xf bank_mask:0xf bound_ctrl:0
	v_fmac_f32_dpp v251, v43, v79 row_shr:2 row_mask:0xf bank_mask:0xf bound_ctrl:0
	v_fmac_f32_dpp v244, v92, v56 row_shl:14 row_mask:0xf bank_mask:0xf bound_ctrl:0
	v_fmac_f32_dpp v245, v93, v57 row_shl:14 row_mask:0xf bank_mask:0xf bound_ctrl:0
	v_fmac_f32_dpp v246, v94, v58 row_shl:14 row_mask:0xf bank_mask:0xf bound_ctrl:0
	v_fmac_f32_dpp v247, v95, v59 row_shl:14 row_mask:0xf bank_mask:0xf bound_ctrl:0
	v_fmac_f32_dpp v248, v88, v76 row_shl:14 row_mask:0xf bank_mask:0xf bound_ctrl:0
	v_fmac_f32_dpp v249, v89, v77 row_shl:14 row_mask:0xf bank_mask:0xf bound_ctrl:0
	v_fmac_f32_dpp v250, v90, v78 row_shl:14 row_mask:0xf bank_mask:0xf bound_ctrl:0
	v_fmac_f32_dpp v251, v91, v79 row_shl:14 row_mask:0xf bank_mask:0xf bound_ctrl:0
	v_fmac_f32_dpp v244, v44, v60 row_shr:1 row_mask:0xf bank_mask:0xf bound_ctrl:0
	v_fmac_f32_dpp v245, v45, v61 row_shr:1 row_mask:0xf bank_mask:0xf bound_ctrl:0
	v_fmac_f32_dpp v246, v46, v62 row_shr:1 row_mask:0xf bank_mask:0xf bound_ctrl:0
	v_fmac_f32_dpp v247, v47, v63 row_shr:1 row_mask:0xf bank_mask:0xf bound_ctrl:0
	v_fmac_f32_dpp v248, v40, v80 row_shr:1 row_mask:0xf bank_mask:0xf bound_ctrl:0
	v_fmac_f32_dpp v249, v41, v81 row_shr:1 row_mask:0xf bank_mask:0xf bound_ctrl:0
	v_fmac_f32_dpp v250, v42, v82 row_shr:1 row_mask:0xf bank_mask:0xf bound_ctrl:0
	v_fmac_f32_dpp v251, v43, v83 row_shr:1 row_mask:0xf bank_mask:0xf bound_ctrl:0
	v_fmac_f32_dpp v244, v92, v60 row_shl:15 row_mask:0xf bank_mask:0xf bound_ctrl:0
	v_fmac_f32_dpp v245, v93, v61 row_shl:15 row_mask:0xf bank_mask:0xf bound_ctrl:0
	v_fmac_f32_dpp v246, v94, v62 row_shl:15 row_mask:0xf bank_mask:0xf bound_ctrl:0
	v_fmac_f32_dpp v247, v95, v63 row_shl:15 row_mask:0xf bank_mask:0xf bound_ctrl:0
	v_fmac_f32_dpp v248, v88, v80 row_shl:15 row_mask:0xf bank_mask:0xf bound_ctrl:0
	v_fmac_f32_dpp v249, v89, v81 row_shl:15 row_mask:0xf bank_mask:0xf bound_ctrl:0
	v_fmac_f32_dpp v250, v90, v82 row_shl:15 row_mask:0xf bank_mask:0xf bound_ctrl:0
	v_fmac_f32_dpp v251, v91, v83 row_shl:15 row_mask:0xf bank_mask:0xf bound_ctrl:0
	v_pk_mul_f32 v[216:217], v[244:245], s[100:101]
	v_pk_mul_f32 v[218:219], v[246:247], s[100:101]
	v_pk_mul_f32 v[220:221], v[248:249], s[100:101]
	v_pk_mul_f32 v[222:223], v[250:251], s[100:101]
	v_exp_f32_e32 v216, v216
	v_exp_f32_e32 v217, v217
	v_exp_f32_e32 v218, v218
	v_exp_f32_e32 v219, v219
	v_exp_f32_e32 v220, v220
	v_exp_f32_e32 v221, v221
	v_exp_f32_e32 v222, v222
	v_exp_f32_e32 v223, v223
	v_pk_add_f32 v[216:217], v[216:217], 1.0 op_sel_hi:[1,0]
	v_pk_add_f32 v[218:219], v[218:219], 1.0 op_sel_hi:[1,0]
	v_pk_add_f32 v[220:221], v[220:221], 1.0 op_sel_hi:[1,0]
	v_pk_add_f32 v[222:223], v[222:223], 1.0 op_sel_hi:[1,0]
	v_rcp_f32_e32 v216, v216
	v_rcp_f32_e32 v217, v217
	v_rcp_f32_e32 v218, v218
	v_rcp_f32_e32 v219, v219
	v_rcp_f32_e32 v220, v220
	v_rcp_f32_e32 v221, v221
	v_rcp_f32_e32 v222, v222
	v_rcp_f32_e32 v223, v223
	v_pk_mul_f32 v[244:245], v[244:245], v[216:217]
	v_pk_mul_f32 v[246:247], v[246:247], v[218:219]
	v_pk_mul_f32 v[248:249], v[248:249], v[220:221]
	v_pk_mul_f32 v[250:251], v[250:251], v[222:223]
	v_pk_mul_f32 v[244:245], v[32:33], v[244:245]
	v_pk_mul_f32 v[246:247], v[34:35], v[246:247]
	v_pk_mul_f32 v[248:249], v[36:37], v[248:249]
	v_pk_mul_f32 v[250:251], v[38:39], v[250:251]
	v_cvt_pk_bf16_f32 v240, v244, v245
	v_cvt_pk_bf16_f32 v241, v246, v247
	v_cvt_pk_bf16_f32 v242, v248, v249
	v_cvt_pk_bf16_f32 v243, v250, v251
	v_lshl_add_u64 v[234:235], v[234:235], 0, v[238:239]
	s_and_b64 s[12:13], s[12:13], s[14:15]
	s_and_saveexec_b64 s[62:63], s[12:13]
	global_store_dwordx4 v[234:235], v[240:243], off
	s_or_b64 exec, exec, s[62:63]
	s_cmp_eq_u64 vcc, 0
	s_cbranch_scc1 .Lgu_nrl5
	global_load_dwordx4 v[76:79], v229, s[50:51] offset:16
	global_load_dwordx4 v[56:59], v229, s[50:51]
	global_load_dwordx4 v[80:83], v229, s[46:47] offset:16
	global_load_dwordx4 v[60:63], v229, s[46:47]
	s_waitcnt vmcnt(0)

.Lgu_nss6:
	v_fma_f32 v244, v64, v28, v52
	v_fma_f32 v245, v65, v29, v53
	v_fma_f32 v246, v66, v30, v54
	v_fma_f32 v247, v67, v31, v55
	v_fma_f32 v248, v84, v24, v72
	v_fma_f32 v249, v85, v25, v73
	v_fma_f32 v250, v86, v26, v74
	v_fma_f32 v251, v87, v27, v75
	v_fmac_f32_dpp v244, v28, v56 row_shr:2 row_mask:0xf bank_mask:0xf bound_ctrl:0
	v_fmac_f32_dpp v245, v29, v57 row_shr:2 row_mask:0xf bank_mask:0xf bound_ctrl:0
	v_fmac_f32_dpp v246, v30, v58 row_shr:2 row_mask:0xf bank_mask:0xf bound_ctrl:0
	v_fmac_f32_dpp v247, v31, v59 row_shr:2 row_mask:0xf bank_mask:0xf bound_ctrl:0
	v_fmac_f32_dpp v248, v24, v76 row_shr:2 row_mask:0xf bank_mask:0xf bound_ctrl:0
	v_fmac_f32_dpp v249, v25, v77 row_shr:2 row_mask:0xf bank_mask:0xf bound_ctrl:0
	v_fmac_f32_dpp v250, v26, v78 row_shr:2 row_mask:0xf bank_mask:0xf bound_ctrl:0
	v_fmac_f32_dpp v251, v27, v79 row_shr:2 row_mask:0xf bank_mask:0xf bound_ctrl:0
	v_fmac_f32_dpp v244, v44, v56 row_shl:14 row_mask:0xf bank_mask:0xf bound_ctrl:0
	v_fmac_f32_dpp v245, v45, v57 row_shl:14 row_mask:0xf bank_mask:0xf bound_ctrl:0
	v_fmac_f32_dpp v246, v46, v58 row_shl:14 row_mask:0xf bank_mask:0xf bound_ctrl:0
	v_fmac_f32_dpp v247, v47, v59 row_shl:14 row_mask:0xf bank_mask:0xf bound_ctrl:0
	v_fmac_f32_dpp v248, v40, v76 row_shl:14 row_mask:0xf bank_mask:0xf bound_ctrl:0
	v_fmac_f32_dpp v249, v41, v77 row_shl:14 row_mask:0xf bank_mask:0xf bound_ctrl:0
	v_fmac_f32_dpp v250, v42, v78 row_shl:14 row_mask:0xf bank_mask:0xf bound_ctrl:0
	v_fmac_f32_dpp v251, v43, v79 row_shl:14 row_mask:0xf bank_mask:0xf bound_ctrl:0
	v_fmac_f32_dpp v244, v28, v60 row_shr:1 row_mask:0xf bank_mask:0xf bound_ctrl:0
	v_fmac_f32_dpp v245, v29, v61 row_shr:1 row_mask:0xf bank_mask:0xf bound_ctrl:0
	v_fmac_f32_dpp v246, v30, v62 row_shr:1 row_mask:0xf bank_mask:0xf bound_ctrl:0
	v_fmac_f32_dpp v247, v31, v63 row_shr:1 row_mask:0xf bank_mask:0xf bound_ctrl:0
	v_fmac_f32_dpp v248, v24, v80 row_shr:1 row_mask:0xf bank_mask:0xf bound_ctrl:0
	v_fmac_f32_dpp v249, v25, v81 row_shr:1 row_mask:0xf bank_mask:0xf bound_ctrl:0
	v_fmac_f32_dpp v250, v26, v82 row_shr:1 row_mask:0xf bank_mask:0xf bound_ctrl:0
	v_fmac_f32_dpp v251, v27, v83 row_shr:1 row_mask:0xf bank_mask:0xf bound_ctrl:0
	v_fmac_f32_dpp v244, v44, v60 row_shl:15 row_mask:0xf bank_mask:0xf bound_ctrl:0
	v_fmac_f32_dpp v245, v45, v61 row_shl:15 row_mask:0xf bank_mask:0xf bound_ctrl:0
	v_fmac_f32_dpp v246, v46, v62 row_shl:15 row_mask:0xf bank_mask:0xf bound_ctrl:0
	v_fmac_f32_dpp v247, v47, v63 row_shl:15 row_mask:0xf bank_mask:0xf bound_ctrl:0
	v_fmac_f32_dpp v248, v40, v80 row_shl:15 row_mask:0xf bank_mask:0xf bound_ctrl:0
	v_fmac_f32_dpp v249, v41, v81 row_shl:15 row_mask:0xf bank_mask:0xf bound_ctrl:0
	v_fmac_f32_dpp v250, v42, v82 row_shl:15 row_mask:0xf bank_mask:0xf bound_ctrl:0
	v_fmac_f32_dpp v251, v43, v83 row_shl:15 row_mask:0xf bank_mask:0xf bound_ctrl:0
	v_pk_mul_f32 v[216:217], v[244:245], s[100:101]
	v_pk_mul_f32 v[218:219], v[246:247], s[100:101]
	v_pk_mul_f32 v[220:221], v[248:249], s[100:101]
	v_pk_mul_f32 v[222:223], v[250:251], s[100:101]
	v_exp_f32_e32 v216, v216
	v_exp_f32_e32 v217, v217
	v_exp_f32_e32 v218, v218
	v_exp_f32_e32 v219, v219
	v_exp_f32_e32 v220, v220
	v_exp_f32_e32 v221, v221
	v_exp_f32_e32 v222, v222
	v_exp_f32_e32 v223, v223
	v_pk_add_f32 v[216:217], v[216:217], 1.0 op_sel_hi:[1,0]
	v_pk_add_f32 v[218:219], v[218:219], 1.0 op_sel_hi:[1,0]
	v_pk_add_f32 v[220:221], v[220:221], 1.0 op_sel_hi:[1,0]
	v_pk_add_f32 v[222:223], v[222:223], 1.0 op_sel_hi:[1,0]
	v_rcp_f32_e32 v216, v216
	v_rcp_f32_e32 v217, v217
	v_rcp_f32_e32 v218, v218
	v_rcp_f32_e32 v219, v219
	v_rcp_f32_e32 v220, v220
	v_rcp_f32_e32 v221, v221
	v_rcp_f32_e32 v222, v222
	v_rcp_f32_e32 v223, v223
	v_pk_mul_f32 v[244:245], v[244:245], v[216:217]
	v_pk_mul_f32 v[246:247], v[246:247], v[218:219]
	v_pk_mul_f32 v[248:249], v[248:249], v[220:221]
	v_pk_mul_f32 v[250:251], v[250:251], v[222:223]
	v_pk_mul_f32 v[244:245], v[16:17], v[244:245]
	v_pk_mul_f32 v[246:247], v[18:19], v[246:247]
	v_pk_mul_f32 v[248:249], v[20:21], v[248:249]
	v_pk_mul_f32 v[250:251], v[22:23], v[250:251]
	v_cvt_pk_bf16_f32 v240, v244, v245
	v_cvt_pk_bf16_f32 v241, v246, v247
	v_cvt_pk_bf16_f32 v242, v248, v249
	v_cvt_pk_bf16_f32 v243, v250, v251
	v_lshl_add_u64 v[234:235], v[234:235], 0, v[238:239]
	s_and_b64 s[12:13], s[12:13], s[14:15]
	s_and_saveexec_b64 s[62:63], s[12:13]
	global_store_dwordx4 v[234:235], v[240:243], off
	s_or_b64 exec, exec, s[62:63]
	s_cmp_eq_u64 vcc, 0
	s_cbranch_scc1 .Lgu_nrl6
	global_load_dwordx4 v[76:79], v229, s[50:51] offset:16
	global_load_dwordx4 v[56:59], v229, s[50:51]
	global_load_dwordx4 v[80:83], v229, s[46:47] offset:16
	global_load_dwordx4 v[60:63], v229, s[46:47]
	s_waitcnt vmcnt(0)

.Lgu_nss7:
	v_fma_f32 v244, v64, v12, v52
	v_fma_f32 v245, v65, v13, v53
	v_fma_f32 v246, v66, v14, v54
	v_fma_f32 v247, v67, v15, v55
	v_fma_f32 v248, v84, v8, v72
	v_fma_f32 v249, v85, v9, v73
	v_fma_f32 v250, v86, v10, v74
	v_fma_f32 v251, v87, v11, v75
	v_fmac_f32_dpp v244, v12, v56 row_shr:2 row_mask:0xf bank_mask:0xf bound_ctrl:0
	v_fmac_f32_dpp v245, v13, v57 row_shr:2 row_mask:0xf bank_mask:0xf bound_ctrl:0
	v_fmac_f32_dpp v246, v14, v58 row_shr:2 row_mask:0xf bank_mask:0xf bound_ctrl:0
	v_fmac_f32_dpp v247, v15, v59 row_shr:2 row_mask:0xf bank_mask:0xf bound_ctrl:0
	v_fmac_f32_dpp v248, v8, v76 row_shr:2 row_mask:0xf bank_mask:0xf bound_ctrl:0
	v_fmac_f32_dpp v249, v9, v77 row_shr:2 row_mask:0xf bank_mask:0xf bound_ctrl:0
	v_fmac_f32_dpp v250, v10, v78 row_shr:2 row_mask:0xf bank_mask:0xf bound_ctrl:0
	v_fmac_f32_dpp v251, v11, v79 row_shr:2 row_mask:0xf bank_mask:0xf bound_ctrl:0
	v_fmac_f32_dpp v244, v28, v56 row_shl:14 row_mask:0xf bank_mask:0xf bound_ctrl:0
	v_fmac_f32_dpp v245, v29, v57 row_shl:14 row_mask:0xf bank_mask:0xf bound_ctrl:0
	v_fmac_f32_dpp v246, v30, v58 row_shl:14 row_mask:0xf bank_mask:0xf bound_ctrl:0
	v_fmac_f32_dpp v247, v31, v59 row_shl:14 row_mask:0xf bank_mask:0xf bound_ctrl:0
	v_fmac_f32_dpp v248, v24, v76 row_shl:14 row_mask:0xf bank_mask:0xf bound_ctrl:0
	v_fmac_f32_dpp v249, v25, v77 row_shl:14 row_mask:0xf bank_mask:0xf bound_ctrl:0
	v_fmac_f32_dpp v250, v26, v78 row_shl:14 row_mask:0xf bank_mask:0xf bound_ctrl:0
	v_fmac_f32_dpp v251, v27, v79 row_shl:14 row_mask:0xf bank_mask:0xf bound_ctrl:0
	v_fmac_f32_dpp v244, v12, v60 row_shr:1 row_mask:0xf bank_mask:0xf bound_ctrl:0
	v_fmac_f32_dpp v245, v13, v61 row_shr:1 row_mask:0xf bank_mask:0xf bound_ctrl:0
	v_fmac_f32_dpp v246, v14, v62 row_shr:1 row_mask:0xf bank_mask:0xf bound_ctrl:0
	v_fmac_f32_dpp v247, v15, v63 row_shr:1 row_mask:0xf bank_mask:0xf bound_ctrl:0
	v_fmac_f32_dpp v248, v8, v80 row_shr:1 row_mask:0xf bank_mask:0xf bound_ctrl:0
	v_fmac_f32_dpp v249, v9, v81 row_shr:1 row_mask:0xf bank_mask:0xf bound_ctrl:0
	v_fmac_f32_dpp v250, v10, v82 row_shr:1 row_mask:0xf bank_mask:0xf bound_ctrl:0
	v_fmac_f32_dpp v251, v11, v83 row_shr:1 row_mask:0xf bank_mask:0xf bound_ctrl:0
	v_fmac_f32_dpp v244, v28, v60 row_shl:15 row_mask:0xf bank_mask:0xf bound_ctrl:0
	v_fmac_f32_dpp v245, v29, v61 row_shl:15 row_mask:0xf bank_mask:0xf bound_ctrl:0
	v_fmac_f32_dpp v246, v30, v62 row_shl:15 row_mask:0xf bank_mask:0xf bound_ctrl:0
	v_fmac_f32_dpp v247, v31, v63 row_shl:15 row_mask:0xf bank_mask:0xf bound_ctrl:0
	v_fmac_f32_dpp v248, v24, v80 row_shl:15 row_mask:0xf bank_mask:0xf bound_ctrl:0
	v_fmac_f32_dpp v249, v25, v81 row_shl:15 row_mask:0xf bank_mask:0xf bound_ctrl:0
	v_fmac_f32_dpp v250, v26, v82 row_shl:15 row_mask:0xf bank_mask:0xf bound_ctrl:0
	v_fmac_f32_dpp v251, v27, v83 row_shl:15 row_mask:0xf bank_mask:0xf bound_ctrl:0
	v_pk_mul_f32 v[216:217], v[244:245], s[100:101]
	v_pk_mul_f32 v[218:219], v[246:247], s[100:101]
	v_pk_mul_f32 v[220:221], v[248:249], s[100:101]
	v_pk_mul_f32 v[222:223], v[250:251], s[100:101]
	v_exp_f32_e32 v216, v216
	v_exp_f32_e32 v217, v217
	v_exp_f32_e32 v218, v218
	v_exp_f32_e32 v219, v219
	v_exp_f32_e32 v220, v220
	v_exp_f32_e32 v221, v221
	v_exp_f32_e32 v222, v222
	v_exp_f32_e32 v223, v223
	v_pk_add_f32 v[216:217], v[216:217], 1.0 op_sel_hi:[1,0]
	v_pk_add_f32 v[218:219], v[218:219], 1.0 op_sel_hi:[1,0]
	v_pk_add_f32 v[220:221], v[220:221], 1.0 op_sel_hi:[1,0]
	v_pk_add_f32 v[222:223], v[222:223], 1.0 op_sel_hi:[1,0]
	v_rcp_f32_e32 v216, v216
	v_rcp_f32_e32 v217, v217
	v_rcp_f32_e32 v218, v218
	v_rcp_f32_e32 v219, v219
	v_rcp_f32_e32 v220, v220
	v_rcp_f32_e32 v221, v221
	v_rcp_f32_e32 v222, v222
	v_rcp_f32_e32 v223, v223
	v_pk_mul_f32 v[244:245], v[244:245], v[216:217]
	v_pk_mul_f32 v[246:247], v[246:247], v[218:219]
	v_pk_mul_f32 v[248:249], v[248:249], v[220:221]
	v_pk_mul_f32 v[250:251], v[250:251], v[222:223]
	v_pk_mul_f32 v[244:245], v[0:1], v[244:245]
	v_pk_mul_f32 v[246:247], v[2:3], v[246:247]
	v_pk_mul_f32 v[248:249], v[4:5], v[248:249]
	v_pk_mul_f32 v[250:251], v[6:7], v[250:251]
	v_cvt_pk_bf16_f32 v240, v244, v245
	v_cvt_pk_bf16_f32 v241, v246, v247
	v_cvt_pk_bf16_f32 v242, v248, v249
	v_cvt_pk_bf16_f32 v243, v250, v251
	v_lshl_add_u64 v[234:235], v[234:235], 0, v[238:239]
	s_and_b64 s[12:13], s[12:13], s[14:15]
	s_and_saveexec_b64 s[62:63], s[12:13]
	global_store_dwordx4 v[234:235], v[240:243], off
	s_or_b64 exec, exec, s[62:63]
	s_cmp_eq_u64 vcc, 0
	s_cbranch_scc1 .Lgu_nrl7
	global_load_dwordx4 v[76:79], v229, s[50:51] offset:16
	global_load_dwordx4 v[56:59], v229, s[50:51]
	global_load_dwordx4 v[80:83], v229, s[46:47] offset:16
	global_load_dwordx4 v[60:63], v229, s[46:47]
	s_waitcnt vmcnt(0)

.LBB0_677:
	s_or_b64 exec, exec, s[62:63]
	s_andn2_b64 vcc, exec, s[8:9]
	s_mov_b64 s[8:9], -1
	s_cbranch_vccnz .LBB0_631
	s_and_b64 vcc, exec, s[10:11]
	s_cbranch_vccnz .LBB0_630
	s_barrier
	s_branch .LBB0_630
.LBB0_695:
	s_waitcnt vmcnt(0)
	s_barrier

.LBB0_770:
	s_add_u32 s38, s38, 0x2b0800
	s_addc_u32 s39, s39, 0
	s_add_u32 s66, s40, 0x1000
	v_mov_b64_e32 v[0:1], 0
	v_mov_b64_e32 v[2:3], 0
	v_mov_b64_e32 v[4:5], 0
	v_mov_b64_e32 v[6:7], 0
	v_mov_b64_e32 v[8:9], 0
	v_mov_b64_e32 v[10:11], 0
	v_mov_b64_e32 v[12:13], 0
	v_mov_b64_e32 v[14:15], 0
	v_mov_b64_e32 v[16:17], 0
	v_mov_b64_e32 v[18:19], 0
	v_mov_b64_e32 v[20:21], 0
	v_mov_b64_e32 v[22:23], 0
	v_mov_b64_e32 v[24:25], 0
	v_mov_b64_e32 v[26:27], 0
	v_mov_b64_e32 v[28:29], 0
	v_mov_b64_e32 v[30:31], 0
	v_mov_b64_e32 v[32:33], 0
	v_mov_b64_e32 v[34:35], 0
	v_mov_b64_e32 v[36:37], 0
	v_mov_b64_e32 v[38:39], 0
	v_mov_b64_e32 v[40:41], 0
	v_mov_b64_e32 v[42:43], 0
	v_mov_b64_e32 v[44:45], 0
	v_mov_b64_e32 v[46:47], 0
	v_mov_b64_e32 v[48:49], 0
	v_mov_b64_e32 v[50:51], 0
	v_mov_b64_e32 v[52:53], 0
	v_mov_b64_e32 v[54:55], 0
	v_mov_b64_e32 v[56:57], 0
	v_mov_b64_e32 v[58:59], 0
	v_mov_b64_e32 v[60:61], 0
	v_mov_b64_e32 v[62:63], 0
	v_mov_b64_e32 v[64:65], 0
	v_mov_b64_e32 v[66:67], 0
	v_mov_b64_e32 v[68:69], 0
	v_mov_b64_e32 v[70:71], 0
	v_mov_b64_e32 v[72:73], 0
	v_mov_b64_e32 v[74:75], 0
	v_mov_b64_e32 v[76:77], 0
	v_mov_b64_e32 v[78:79], 0
	v_mov_b64_e32 v[80:81], 0
	v_mov_b64_e32 v[82:83], 0
	v_mov_b64_e32 v[84:85], 0
	v_mov_b64_e32 v[86:87], 0
	v_mov_b64_e32 v[88:89], 0
	v_mov_b64_e32 v[90:91], 0
	v_mov_b64_e32 v[92:93], 0
	v_mov_b64_e32 v[94:95], 0
	v_mov_b64_e32 v[96:97], 0
	v_mov_b64_e32 v[98:99], 0
	v_mov_b64_e32 v[100:101], 0
	v_mov_b64_e32 v[102:103], 0
	v_mov_b64_e32 v[104:105], 0
	v_mov_b64_e32 v[106:107], 0
	v_mov_b64_e32 v[108:109], 0
	v_mov_b64_e32 v[110:111], 0
	v_mov_b64_e32 v[112:113], 0
	v_mov_b64_e32 v[114:115], 0
	v_mov_b64_e32 v[116:117], 0
	v_mov_b64_e32 v[118:119], 0
	v_mov_b64_e32 v[120:121], 0
	v_mov_b64_e32 v[122:123], 0
	v_mov_b64_e32 v[124:125], 0
	v_mov_b64_e32 v[126:127], 0
	s_addc_u32 s67, s41, 0
	s_mov_b32 s68, -2
	s_waitcnt lgkmcnt(0)
